# v25: v23 + streaming (nt) cache hint on the FF2 epilogue's f32 output stores (written once, never re-read in the kernel)
# baseline (speedup 1.0000x reference)
; #define PG8_STAGE(bufoff, gbase, voff) do { _Pragma("unroll") for (int _i = 0; _i < 2; ++_i) \
;         __builtin_amdgcn_global_load_lds((const unsigned*)((const char*)(gbase) + (voff)[_i]), (LAS unsigned*)(lds + (bufoff) + ldsw + _i * 8192), 16, 0, 0); } while (0)
; #define PG8_LDA(dst, b, h) do { _Pragma("unroll") for (int m = 0; m < 4; ++m) _Pragma("unroll") for (int k = 0; k < 2; ++k) dst[m][k] = *(const LAS bf16x8*)(lds + PG8_SA(b, h) + aoff + m * 2048 + k * 1024); } while (0)
; #define PG8_LDB(dst, b, h) do { _Pragma("unroll") for (int n = 0; n < 2; ++n) _Pragma("unroll") for (int k = 0; k < 2; ++k) dst[n][k] = *(const LAS bf16x8*)(lds + PG8_SB(b, h) + boff + n * 2048 + k * 1024); } while (0)
; #define PG8_WAIT_V(n) asm volatile("s_waitcnt vmcnt(" #n ")" ::: "memory")
; #define PG8_WAIT_L(n) asm volatile("s_waitcnt lgkmcnt(" #n ")" ::: "memory")
; #define PG8_BAR __builtin_amdgcn_s_barrier()
; #define PG8_SCHED __builtin_amdgcn_sched_barrier(0)
; template <class Epi, class Ptrs>
; __device__ __forceinline__ void gemm_phase(LAS unsigned char* lds, const int K, const StaticOrder& S, const Ptrs& P, const Epi& E) {
;     ...
;         for (int t = 0; t < nt; t += 2) {
;             const bool last = (t == nt - 2);
;             const char* a1 = cA + (size_t)(t + 1) * kstep;
;             const char* a2 = last ? nA : cA + (size_t)(t + 2) * kstep; const char* b2 = last ? nB : cB + (size_t)(t + 2) * kstep;
;             const char* a3 = a2 + kstep; const char* b3 = b2 + kstep;
;             PG8_LDB(B0, 0, 0); PG8_SCHED; PG8_LDA(At, 0, 0); PG8_STAGE(PG8_SA(1, 1), a1 + hstep, voffA);
;             PG8_WAIT_L(8); PG8_BAR; PG8_WAIT_L(0); PG8_MMA(0, 0, At, B0); PG8_BAR; PG8_SCHED;
;             PG8_LDB(B1, 0, 1); PG8_STAGE(PG8_SB(0, 0), b2, voffB);
;             PG8_BAR; PG8_WAIT_L(0); PG8_MMA(0, 1, At, B1); PG8_BAR;
;             PG8_LDA(At, 0, 1); PG8_STAGE(PG8_SA(0, 0), a2, voffA);
;             PG8_BAR; PG8_WAIT_L(0); PG8_MMA(1, 0, At, B0); PG8_BAR; PG8_SCHED;
;             PG8_STAGE(PG8_SB(0, 1), b2 + hstep, voffB);
;             PG8_WAIT_V(6); PG8_BAR; PG8_MMA(1, 1, At, B1); PG8_BAR;
;             PG8_LDB(B0, 1, 0); PG8_SCHED; PG8_LDA(At, 1, 0); PG8_STAGE(PG8_SA(0, 1), a2 + hstep, voffA);
;             PG8_WAIT_L(8); PG8_BAR; PG8_WAIT_L(0); PG8_MMA(0, 0, At, B0); PG8_BAR; PG8_SCHED;
.LBB0_522:
	ds_read_b128 v[128:131], v193
	ds_read_b128 v[132:135], v193 offset:1024
	ds_read_b128 v[136:139], v193 offset:2048
	ds_read_b128 v[140:143], v193 offset:3072
	s_add_u32 s22, s20, 0xfff00080
	s_addc_u32 s23, s21, -1
	s_cmp_eq_u32 s46, 60
	s_cselect_b32 s25, s5, s23
	s_cselect_b32 s24, s4, s22
	s_cselect_b32 s23, s15, s13
	s_cselect_b32 s22, s14, s11
	s_add_i32 m0, s17, 0xc000
	ds_read_b128 v[144:147], v194
	ds_read_b128 v[148:151], v194 offset:1024
	ds_read_b128 v[152:155], v194 offset:2048
	ds_read_b128 v[156:159], v194 offset:3072
	ds_read_b128 v[176:179], v194 offset:4096
	ds_read_b128 v[180:183], v194 offset:5120
	ds_read_b128 v[196:199], v194 offset:6144
	ds_read_b128 v[200:203], v194 offset:7168
	global_load_lds_dwordx4 v168, s[20:21]
	s_add_i32 m0, s17, 0xe000
	s_nop 0
	global_load_lds_dwordx4 v170, s[20:21]
	s_waitcnt lgkmcnt(8)
	s_barrier
	s_waitcnt lgkmcnt(0)
	v_mfma_f32_16x16x32_bf16 v[124:127], v[128:131], v[144:147], v[124:127]
	v_mfma_f32_16x16x32_bf16 v[124:127], v[132:135], v[148:151], v[124:127]
	v_mfma_f32_16x16x32_bf16 v[120:123], v[140:143], v[148:151], v[120:123]
	v_mfma_f32_16x16x32_bf16 v[120:123], v[136:139], v[144:147], v[120:123]
	v_mfma_f32_16x16x32_bf16 v[104:107], v[136:139], v[152:155], v[104:107]
	v_mfma_f32_16x16x32_bf16 v[104:107], v[140:143], v[156:159], v[104:107]
	v_mfma_f32_16x16x32_bf16 v[112:115], v[132:135], v[156:159], v[112:115]
	v_mfma_f32_16x16x32_bf16 v[112:115], v[128:131], v[152:155], v[112:115]
	v_mfma_f32_16x16x32_bf16 v[92:95], v[128:131], v[176:179], v[92:95]
	v_mfma_f32_16x16x32_bf16 v[92:95], v[132:135], v[180:183], v[92:95]
	v_mfma_f32_16x16x32_bf16 v[88:91], v[140:143], v[180:183], v[88:91]
	v_mfma_f32_16x16x32_bf16 v[88:91], v[136:139], v[176:179], v[88:91]
	v_mfma_f32_16x16x32_bf16 v[72:75], v[136:139], v[196:199], v[72:75]
	v_mfma_f32_16x16x32_bf16 v[72:75], v[140:143], v[200:203], v[72:75]
	v_mfma_f32_16x16x32_bf16 v[76:79], v[132:135], v[200:203], v[76:79]
	v_mfma_f32_16x16x32_bf16 v[76:79], v[128:131], v[196:199], v[76:79]
	s_barrier
	s_add_i32 s47, s42, s34
	s_add_u32 s90, s22, 0x80
	s_addc_u32 s91, s23, 0
	s_mov_b32 m0, s47
	ds_read_b128 v[204:207], v195
	ds_read_b128 v[208:211], v195 offset:1024
	ds_read_b128 v[212:215], v195 offset:2048
	ds_read_b128 v[216:219], v195 offset:3072
	global_load_lds_dwordx4 v162, s[22:23]
	s_add_i32 m0, s47, 0x2000
	s_nop 0
	global_load_lds_dwordx4 v166, s[22:23]
	s_barrier
	s_waitcnt lgkmcnt(0)
	v_mfma_f32_16x16x32_bf16 v[116:119], v[204:207], v[144:147], v[116:119]
	v_mfma_f32_16x16x32_bf16 v[116:119], v[208:211], v[148:151], v[116:119]
	v_mfma_f32_16x16x32_bf16 v[108:111], v[216:219], v[148:151], v[108:111]
	v_mfma_f32_16x16x32_bf16 v[108:111], v[212:215], v[144:147], v[108:111]
	v_mfma_f32_16x16x32_bf16 v[96:99], v[212:215], v[152:155], v[96:99]
	v_mfma_f32_16x16x32_bf16 v[96:99], v[216:219], v[156:159], v[96:99]
	v_mfma_f32_16x16x32_bf16 v[100:103], v[208:211], v[156:159], v[100:103]
	v_mfma_f32_16x16x32_bf16 v[100:103], v[204:207], v[152:155], v[100:103]
	v_mfma_f32_16x16x32_bf16 v[84:87], v[204:207], v[176:179], v[84:87]
	v_mfma_f32_16x16x32_bf16 v[84:87], v[208:211], v[180:183], v[84:87]
	v_mfma_f32_16x16x32_bf16 v[80:83], v[216:219], v[180:183], v[80:83]
	v_mfma_f32_16x16x32_bf16 v[80:83], v[212:215], v[176:179], v[80:83]
	v_mfma_f32_16x16x32_bf16 v[64:67], v[212:215], v[196:199], v[64:67]
	v_mfma_f32_16x16x32_bf16 v[64:67], v[216:219], v[200:203], v[64:67]
	v_mfma_f32_16x16x32_bf16 v[68:71], v[208:211], v[200:203], v[68:71]
	v_mfma_f32_16x16x32_bf16 v[68:71], v[204:207], v[196:199], v[68:71]
	s_barrier
	s_mov_b32 m0, s17
	s_add_u32 s92, s24, 0x80
	s_addc_u32 s93, s25, 0
	ds_read_b128 v[144:147], v194 offset:16384
	ds_read_b128 v[148:151], v194 offset:17408
	ds_read_b128 v[152:155], v194 offset:18432
	ds_read_b128 v[156:159], v194 offset:19456
	ds_read_b128 v[176:179], v194 offset:20480
	ds_read_b128 v[180:183], v194 offset:21504
	ds_read_b128 v[196:199], v194 offset:22528
	ds_read_b128 v[200:203], v194 offset:23552
	global_load_lds_dwordx4 v160, s[24:25]
	s_mov_b32 m0, s19
	s_nop 0
	global_load_lds_dwordx4 v164, s[24:25]
	s_barrier
	s_waitcnt lgkmcnt(0)
	v_mfma_f32_16x16x32_bf16 v[60:63], v[128:131], v[144:147], v[60:63]
	v_mfma_f32_16x16x32_bf16 v[60:63], v[132:135], v[148:151], v[60:63]
	v_mfma_f32_16x16x32_bf16 v[56:59], v[140:143], v[148:151], v[56:59]
	v_mfma_f32_16x16x32_bf16 v[56:59], v[136:139], v[144:147], v[56:59]
	v_mfma_f32_16x16x32_bf16 v[40:43], v[136:139], v[152:155], v[40:43]
	v_mfma_f32_16x16x32_bf16 v[40:43], v[140:143], v[156:159], v[40:43]
	v_mfma_f32_16x16x32_bf16 v[48:51], v[132:135], v[156:159], v[48:51]
	v_mfma_f32_16x16x32_bf16 v[48:51], v[128:131], v[152:155], v[48:51]
	v_mfma_f32_16x16x32_bf16 v[32:35], v[128:131], v[176:179], v[32:35]
	v_mfma_f32_16x16x32_bf16 v[32:35], v[132:135], v[180:183], v[32:35]
	v_mfma_f32_16x16x32_bf16 v[24:27], v[140:143], v[180:183], v[24:27]
	v_mfma_f32_16x16x32_bf16 v[24:27], v[136:139], v[176:179], v[24:27]
	v_mfma_f32_16x16x32_bf16 v[8:11], v[136:139], v[196:199], v[8:11]
	v_mfma_f32_16x16x32_bf16 v[8:11], v[140:143], v[200:203], v[8:11]
	v_mfma_f32_16x16x32_bf16 v[16:19], v[132:135], v[200:203], v[16:19]
	v_mfma_f32_16x16x32_bf16 v[16:19], v[128:131], v[196:199], v[16:19]
	s_barrier
	s_add_u32 s48, s22, 0x100000
	s_addc_u32 s49, s23, 0
	s_add_i32 s47, s43, s34
	s_mov_b32 m0, s47
	s_nop 0
	global_load_lds_dwordx4 v162, s[48:49]
	s_add_i32 m0, s47, 0x2000
	s_nop 0
	global_load_lds_dwordx4 v166, s[48:49]
	s_waitcnt vmcnt(6)
	s_barrier
; #define PG8_STAGE(bufoff, gbase, voff) do { _Pragma("unroll") for (int _i = 0; _i < 2; ++_i) \
;         __builtin_amdgcn_global_load_lds((const unsigned*)((const char*)(gbase) + (voff)[_i]), (LAS unsigned*)(lds + (bufoff) + ldsw + _i * 8192), 16, 0, 0); } while (0)
; #define PG8_LDA(dst, b, h) do { _Pragma("unroll") for (int m = 0; m < 4; ++m) _Pragma("unroll") for (int k = 0; k < 2; ++k) dst[m][k] = *(const LAS bf16x8*)(lds + PG8_SA(b, h) + aoff + m * 2048 + k * 1024); } while (0)
; #define PG8_LDB(dst, b, h) do { _Pragma("unroll") for (int n = 0; n < 2; ++n) _Pragma("unroll") for (int k = 0; k < 2; ++k) dst[n][k] = *(const LAS bf16x8*)(lds + PG8_SB(b, h) + boff + n * 2048 + k * 1024); } while (0)
; #define PG8_MMA(ai, bj, At, Bt) do { __builtin_amdgcn_s_setprio(1); _Pragma("unroll") for (int m = 0; m < 4; ++m) _Pragma("unroll") for (int n = 0; n < 2; ++n) _Pragma("unroll") for (int k = 0; k < 2; ++k) \
;         acc[ai][bj][m][n] = __builtin_amdgcn_mfma_f32_16x16x32_bf16(Bt[n][k], At[m][k], acc[ai][bj][m][n], 0, 0, 0); __builtin_amdgcn_s_setprio(0); } while (0)
; #define PG8_WAIT_V(n) asm volatile("s_waitcnt vmcnt(" #n ")" ::: "memory")
; #define PG8_WAIT_L(n) asm volatile("s_waitcnt lgkmcnt(" #n ")" ::: "memory")
; #define PG8_BAR __builtin_amdgcn_s_barrier()
; #define PG8_SCHED __builtin_amdgcn_sched_barrier(0)
; template <class Epi, class Ptrs>
; __device__ __forceinline__ void gemm_phase(LAS unsigned char* lds, const int K, const StaticOrder& S, const Ptrs& P, const Epi& E) {
;     ...
;             PG8_WAIT_V(6); PG8_BAR; PG8_MMA(1, 1, At, B1); PG8_BAR;
;             PG8_LDB(B0, 1, 0); PG8_SCHED; PG8_LDA(At, 1, 0); PG8_STAGE(PG8_SA(0, 1), a2 + hstep, voffA);
;             PG8_WAIT_L(8); PG8_BAR; PG8_WAIT_L(0); PG8_MMA(0, 0, At, B0); PG8_BAR; PG8_SCHED;
;             PG8_LDB(B1, 1, 1); PG8_STAGE(PG8_SB(1, 0), b3, voffB);
;             PG8_BAR; PG8_WAIT_L(0); PG8_MMA(0, 1, At, B1); PG8_BAR;
;             PG8_LDA(At, 1, 1); PG8_STAGE(PG8_SA(1, 0), a3, voffA);
;             PG8_BAR; PG8_WAIT_L(0); PG8_MMA(1, 0, At, B0); PG8_BAR; PG8_SCHED;
;             PG8_STAGE(PG8_SB(1, 1), b3 + hstep, voffB);
;             PG8_WAIT_V(6); PG8_BAR; PG8_MMA(1, 1, At, B1); PG8_BAR;
	v_mfma_f32_16x16x32_bf16 v[52:55], v[204:207], v[144:147], v[52:55]
	v_mfma_f32_16x16x32_bf16 v[52:55], v[208:211], v[148:151], v[52:55]
	v_mfma_f32_16x16x32_bf16 v[44:47], v[216:219], v[148:151], v[44:47]
	v_mfma_f32_16x16x32_bf16 v[44:47], v[212:215], v[144:147], v[44:47]
	v_mfma_f32_16x16x32_bf16 v[28:31], v[212:215], v[152:155], v[28:31]
	v_mfma_f32_16x16x32_bf16 v[28:31], v[216:219], v[156:159], v[28:31]
	v_mfma_f32_16x16x32_bf16 v[36:39], v[208:211], v[156:159], v[36:39]
	v_mfma_f32_16x16x32_bf16 v[36:39], v[204:207], v[152:155], v[36:39]
	v_mfma_f32_16x16x32_bf16 v[20:23], v[204:207], v[176:179], v[20:23]
	v_mfma_f32_16x16x32_bf16 v[20:23], v[208:211], v[180:183], v[20:23]
	v_mfma_f32_16x16x32_bf16 v[12:15], v[216:219], v[180:183], v[12:15]
	v_mfma_f32_16x16x32_bf16 v[12:15], v[212:215], v[176:179], v[12:15]
	v_mfma_f32_16x16x32_bf16 v[0:3], v[212:215], v[196:199], v[0:3]
	v_mfma_f32_16x16x32_bf16 v[0:3], v[216:219], v[200:203], v[0:3]
	v_mfma_f32_16x16x32_bf16 v[4:7], v[208:211], v[200:203], v[4:7]
	v_mfma_f32_16x16x32_bf16 v[4:7], v[204:207], v[196:199], v[4:7]
	s_barrier
	s_add_i32 s47, 0, 0x18000
	ds_read_b128 v[128:131], v252
	ds_read_b128 v[132:135], v252 offset:1024
	ds_read_b128 v[136:139], v252 offset:2048
	ds_read_b128 v[140:143], v252 offset:3072
	s_add_u32 s24, s24, 0x100000
	s_addc_u32 s25, s25, 0
	s_mov_b32 m0, s40
	ds_read_b128 v[144:147], v194 offset:32768
	ds_read_b128 v[148:151], v194 offset:33792
	ds_read_b128 v[152:155], v194 offset:34816
	ds_read_b128 v[156:159], v194 offset:35840
	ds_read_b128 v[176:179], v194 offset:36864
	ds_read_b128 v[180:183], v194 offset:37888
	ds_read_b128 v[196:199], v194 offset:38912
	ds_read_b128 v[200:203], v194 offset:39936
	global_load_lds_dwordx4 v160, s[24:25]
	s_mov_b32 m0, s41
	s_nop 0
	global_load_lds_dwordx4 v164, s[24:25]
	s_waitcnt lgkmcnt(8)
	s_barrier
	s_waitcnt lgkmcnt(0)
	v_mfma_f32_16x16x32_bf16 v[124:127], v[128:131], v[144:147], v[124:127]
	v_mfma_f32_16x16x32_bf16 v[124:127], v[132:135], v[148:151], v[124:127]
	v_mfma_f32_16x16x32_bf16 v[120:123], v[140:143], v[148:151], v[120:123]
	v_mfma_f32_16x16x32_bf16 v[120:123], v[136:139], v[144:147], v[120:123]
	v_mfma_f32_16x16x32_bf16 v[104:107], v[136:139], v[152:155], v[104:107]
	v_mfma_f32_16x16x32_bf16 v[104:107], v[140:143], v[156:159], v[104:107]
	v_mfma_f32_16x16x32_bf16 v[112:115], v[132:135], v[156:159], v[112:115]
	v_mfma_f32_16x16x32_bf16 v[112:115], v[128:131], v[152:155], v[112:115]
	v_mfma_f32_16x16x32_bf16 v[92:95], v[128:131], v[176:179], v[92:95]
	v_mfma_f32_16x16x32_bf16 v[92:95], v[132:135], v[180:183], v[92:95]
	v_mfma_f32_16x16x32_bf16 v[88:91], v[140:143], v[180:183], v[88:91]
	v_mfma_f32_16x16x32_bf16 v[88:91], v[136:139], v[176:179], v[88:91]
	v_mfma_f32_16x16x32_bf16 v[72:75], v[136:139], v[196:199], v[72:75]
	v_mfma_f32_16x16x32_bf16 v[72:75], v[140:143], v[200:203], v[72:75]
	v_mfma_f32_16x16x32_bf16 v[76:79], v[132:135], v[200:203], v[76:79]
	v_mfma_f32_16x16x32_bf16 v[76:79], v[128:131], v[196:199], v[76:79]
	s_barrier
	s_add_i32 s24, 0, 0x1c000
	s_add_i32 s25, s47, s34
	s_mov_b32 m0, s25
	ds_read_b128 v[204:207], v253
	ds_read_b128 v[208:211], v253 offset:1024
	ds_read_b128 v[212:215], v253 offset:2048
	ds_read_b128 v[216:219], v253 offset:3072
	global_load_lds_dwordx4 v162, s[90:91]
	s_add_i32 m0, s25, 0x2000
	s_nop 0
	global_load_lds_dwordx4 v166, s[90:91]
	s_barrier
	s_waitcnt lgkmcnt(0)
	v_mfma_f32_16x16x32_bf16 v[116:119], v[204:207], v[144:147], v[116:119]
	v_mfma_f32_16x16x32_bf16 v[116:119], v[208:211], v[148:151], v[116:119]
	v_mfma_f32_16x16x32_bf16 v[108:111], v[216:219], v[148:151], v[108:111]
	v_mfma_f32_16x16x32_bf16 v[108:111], v[212:215], v[144:147], v[108:111]
	v_mfma_f32_16x16x32_bf16 v[96:99], v[212:215], v[152:155], v[96:99]
	v_mfma_f32_16x16x32_bf16 v[96:99], v[216:219], v[156:159], v[96:99]
	v_mfma_f32_16x16x32_bf16 v[100:103], v[208:211], v[156:159], v[100:103]
	v_mfma_f32_16x16x32_bf16 v[100:103], v[204:207], v[152:155], v[100:103]
	v_mfma_f32_16x16x32_bf16 v[84:87], v[204:207], v[176:179], v[84:87]
	v_mfma_f32_16x16x32_bf16 v[84:87], v[208:211], v[180:183], v[84:87]
	v_mfma_f32_16x16x32_bf16 v[80:83], v[216:219], v[180:183], v[80:83]
	v_mfma_f32_16x16x32_bf16 v[80:83], v[212:215], v[176:179], v[80:83]
	v_mfma_f32_16x16x32_bf16 v[64:67], v[212:215], v[196:199], v[64:67]
	v_mfma_f32_16x16x32_bf16 v[64:67], v[216:219], v[200:203], v[64:67]
	v_mfma_f32_16x16x32_bf16 v[68:71], v[208:211], v[200:203], v[68:71]
	v_mfma_f32_16x16x32_bf16 v[68:71], v[204:207], v[196:199], v[68:71]
	s_barrier
	s_mov_b32 m0, s28
	ds_read_b128 v[144:147], v194 offset:49152
	ds_read_b128 v[148:151], v194 offset:50176
	ds_read_b128 v[152:155], v194 offset:51200
	ds_read_b128 v[156:159], v194 offset:52224
	ds_read_b128 v[176:179], v194 offset:53248
	ds_read_b128 v[180:183], v194 offset:54272
	ds_read_b128 v[196:199], v194 offset:55296
	ds_read_b128 v[200:203], v194 offset:56320
	global_load_lds_dwordx4 v160, s[92:93]
	s_mov_b32 m0, s29
	s_nop 0
	global_load_lds_dwordx4 v164, s[92:93]
	s_barrier
	s_waitcnt lgkmcnt(0)
	v_mfma_f32_16x16x32_bf16 v[60:63], v[128:131], v[144:147], v[60:63]
	v_mfma_f32_16x16x32_bf16 v[60:63], v[132:135], v[148:151], v[60:63]
	v_mfma_f32_16x16x32_bf16 v[56:59], v[140:143], v[148:151], v[56:59]
	v_mfma_f32_16x16x32_bf16 v[56:59], v[136:139], v[144:147], v[56:59]
	v_mfma_f32_16x16x32_bf16 v[40:43], v[136:139], v[152:155], v[40:43]
	v_mfma_f32_16x16x32_bf16 v[40:43], v[140:143], v[156:159], v[40:43]
	v_mfma_f32_16x16x32_bf16 v[48:51], v[132:135], v[156:159], v[48:51]
	v_mfma_f32_16x16x32_bf16 v[48:51], v[128:131], v[152:155], v[48:51]
	v_mfma_f32_16x16x32_bf16 v[32:35], v[128:131], v[176:179], v[32:35]
	v_mfma_f32_16x16x32_bf16 v[32:35], v[132:135], v[180:183], v[32:35]
	v_mfma_f32_16x16x32_bf16 v[24:27], v[140:143], v[180:183], v[24:27]
	v_mfma_f32_16x16x32_bf16 v[24:27], v[136:139], v[176:179], v[24:27]
	v_mfma_f32_16x16x32_bf16 v[8:11], v[136:139], v[196:199], v[8:11]
	v_mfma_f32_16x16x32_bf16 v[8:11], v[140:143], v[200:203], v[8:11]
	v_mfma_f32_16x16x32_bf16 v[16:19], v[132:135], v[200:203], v[16:19]
	v_mfma_f32_16x16x32_bf16 v[16:19], v[128:131], v[196:199], v[16:19]
	s_barrier
; __device__ __forceinline__ float bf_lo(unsigned w) { return __uint_as_float(w << 16); }
; __device__ __forceinline__ float bf_hi(unsigned w) { return __uint_as_float(w & 0xffff0000u); }
; #define PG8_STAGE(bufoff, gbase, voff) do { _Pragma("unroll") for (int _i = 0; _i < 2; ++_i) \
;         __builtin_amdgcn_global_load_lds((const unsigned*)((const char*)(gbase) + (voff)[_i]), (LAS unsigned*)(lds + (bufoff) + ldsw + _i * 8192), 16, 0, 0); } while (0)
; #define PG8_MMA(ai, bj, At, Bt) do { __builtin_amdgcn_s_setprio(1); _Pragma("unroll") for (int m = 0; m < 4; ++m) _Pragma("unroll") for (int n = 0; n < 2; ++n) _Pragma("unroll") for (int k = 0; k < 2; ++k) \
;         acc[ai][bj][m][n] = __builtin_amdgcn_mfma_f32_16x16x32_bf16(Bt[n][k], At[m][k], acc[ai][bj][m][n], 0, 0, 0); __builtin_amdgcn_s_setprio(0); } while (0)
; #define PG8_WAIT_V(n) asm volatile("s_waitcnt vmcnt(" #n ")" ::: "memory")
; #define PG8_BAR __builtin_amdgcn_s_barrier()
; template <class Epi, class Ptrs>
; __device__ __forceinline__ void gemm_phase(LAS unsigned char* lds, const int K, const StaticOrder& S, const Ptrs& P, const Epi& E) {
;     ...
;             PG8_BAR; PG8_WAIT_L(0); PG8_MMA(1, 0, At, B0); PG8_BAR; PG8_SCHED;
;             PG8_STAGE(PG8_SB(1, 1), b3 + hstep, voffB);
;             PG8_WAIT_V(6); PG8_BAR; PG8_MMA(1, 1, At, B1); PG8_BAR;
;     __device__ __forceinline__ void operator()(const f32x4 (&acc)[2][2][4][2], const Unit& u, int ui, int wr, int wc, int fr, int fq) const {
;         const int rl0 = wr * 64 + fr, col0 = u.pn * 256 + wc * 32 + 8 * fq;
;         u32x4 xv[2][4][2];
; #pragma unroll
;         for (int ai = 0; ai < 2; ++ai)
; #pragma unroll
;             for (int m = 0; m < 4; ++m)
; #pragma unroll
;                 for (int bj = 0; bj < 2; ++bj) xv[ai][m][bj] = *(const u32x4*)(xb + (size_t)(u.pm * 256 + rl0 + ai * 128 + m * 16) * DM + col0 + bj * 128);
; #pragma unroll
;         for (int ai = 0; ai < 2; ++ai)
; #pragma unroll
;             for (int m = 0; m < 4; ++m) { const int rl = rl0 + ai * 128 + m * 16; float* rowp = out + (size_t)(u.pm * 256 + rl) * DM + col0;
;                 const float r2 = tab[ui * 256 + rl];
; #pragma unroll
;                 for (int bj = 0; bj < 2; ++bj) { const u32x4 x = xv[ai][m][bj];
;                     const f32x4 x0 = {bf_lo(x.x), bf_hi(x.x), bf_lo(x.y), bf_hi(x.y)}, x1 = {bf_lo(x.z), bf_hi(x.z), bf_lo(x.w), bf_hi(x.w)};
	s_add_u32 s22, s22, 0x100080
	s_addc_u32 s23, s23, 0
	s_add_i32 s24, s24, s34
	s_mov_b32 m0, s24
	s_nop 0
	global_load_lds_dwordx4 v162, s[22:23]
	s_add_i32 m0, s24, 0x2000
	s_nop 0
	global_load_lds_dwordx4 v166, s[22:23]
	s_waitcnt vmcnt(6)
	s_barrier
	v_mfma_f32_16x16x32_bf16 v[52:55], v[204:207], v[144:147], v[52:55]
	v_mfma_f32_16x16x32_bf16 v[52:55], v[208:211], v[148:151], v[52:55]
	v_mfma_f32_16x16x32_bf16 v[44:47], v[216:219], v[148:151], v[44:47]
	v_mfma_f32_16x16x32_bf16 v[44:47], v[212:215], v[144:147], v[44:47]
	v_mfma_f32_16x16x32_bf16 v[28:31], v[212:215], v[152:155], v[28:31]
	v_mfma_f32_16x16x32_bf16 v[28:31], v[216:219], v[156:159], v[28:31]
	v_mfma_f32_16x16x32_bf16 v[36:39], v[208:211], v[156:159], v[36:39]
	v_mfma_f32_16x16x32_bf16 v[36:39], v[204:207], v[152:155], v[36:39]
	v_mfma_f32_16x16x32_bf16 v[20:23], v[204:207], v[176:179], v[20:23]
	v_mfma_f32_16x16x32_bf16 v[20:23], v[208:211], v[180:183], v[20:23]
	v_mfma_f32_16x16x32_bf16 v[12:15], v[216:219], v[180:183], v[12:15]
	v_mfma_f32_16x16x32_bf16 v[12:15], v[212:215], v[176:179], v[12:15]
	v_mfma_f32_16x16x32_bf16 v[0:3], v[212:215], v[196:199], v[0:3]
	v_mfma_f32_16x16x32_bf16 v[0:3], v[216:219], v[200:203], v[0:3]
	v_mfma_f32_16x16x32_bf16 v[4:7], v[208:211], v[200:203], v[4:7]
	v_mfma_f32_16x16x32_bf16 v[4:7], v[204:207], v[196:199], v[4:7]
	s_barrier
	s_add_i32 s46, s46, 2
	s_add_u32 s20, s20, 0x100
	s_addc_u32 s21, s21, 0
	s_add_u32 s11, s11, 0x100
	s_addc_u32 s13, s13, 0
	s_cmp_gt_u32 s46, 61
	s_cbranch_scc0 .LBB0_522
	s_lshl_b32 s11, s18, 8
	v_lshl_or_b32 v128, s16, 8, v191
	v_add_u32_e32 v130, s11, v186
	v_ashrrev_i32_e32 v129, 31, v128
	v_ashrrev_i32_e32 v131, 31, v130
	v_lshl_add_u64 v[132:133], v[128:129], 1, s[6:7]
	v_lshlrev_b64 v[134:135], 11, v[130:131]
	v_lshl_add_u64 v[134:135], v[132:133], 0, v[134:135]
	global_load_dwordx4 v[198:201], v[134:135], off
	global_load_dwordx4 v[202:205], v[134:135], off offset:256
	v_or_b32_e32 v134, 16, v130
	v_ashrrev_i32_e32 v135, 31, v134
	v_lshlrev_b64 v[134:135], 11, v[134:135]
	v_lshl_add_u64 v[134:135], v[132:133], 0, v[134:135]
	global_load_dwordx4 v[206:209], v[134:135], off
	global_load_dwordx4 v[210:213], v[134:135], off offset:256
	v_or_b32_e32 v136, 32, v130
	v_ashrrev_i32_e32 v137, 31, v136
	v_or_b32_e32 v138, 48, v130
	v_add_u32_e32 v184, 0x80, v130
	v_add_u32_e32 v182, 0x90, v130
	v_add_u32_e32 v180, 0xa0, v130
	v_add_u32_e32 v178, 0xb0, v130
	v_lshlrev_b64 v[176:177], 2, v[128:129]
	v_lshlrev_b64 v[128:129], 12, v[130:131]
	v_lshlrev_b64 v[130:131], 11, v[136:137]
	v_lshl_add_u64 v[130:131], v[132:133], 0, v[130:131]
	global_load_dwordx4 v[214:217], v[130:131], off
	v_ashrrev_i32_e32 v139, 31, v138
	v_ashrrev_i32_e32 v185, 31, v184
	v_ashrrev_i32_e32 v183, 31, v182
	v_ashrrev_i32_e32 v181, 31, v180
	v_ashrrev_i32_e32 v179, 31, v178
	v_lshlrev_b64 v[134:135], 11, v[138:139]
	v_lshlrev_b64 v[136:137], 11, v[184:185]
	v_lshlrev_b64 v[138:139], 11, v[182:183]
	v_lshl_add_u32 v196, s45, 10, v192
	v_lshlrev_b64 v[140:141], 11, v[180:181]
	v_lshlrev_b64 v[142:143], 11, v[178:179]
	v_lshl_add_u64 v[128:129], s[26:27], 0, v[128:129]
	v_lshl_add_u64 v[134:135], v[132:133], 0, v[134:135]
	v_lshl_add_u64 v[136:137], v[132:133], 0, v[136:137]
	v_lshl_add_u64 v[138:139], v[132:133], 0, v[138:139]
	ds_read2_b32 v[230:231], v196 offset1:16
	v_lshl_add_u64 v[234:235], v[132:133], 0, v[140:141]
	v_lshl_add_u64 v[236:237], v[132:133], 0, v[142:143]
	v_lshl_add_u64 v[238:239], v[128:129], 0, v[176:177]
	global_load_dwordx4 v[218:221], v[130:131], off offset:256
	global_load_dwordx4 v[222:225], v[134:135], off
	global_load_dwordx4 v[226:229], v[134:135], off offset:256
	global_load_dwordx4 v[156:159], v[136:137], off
	global_load_dwordx4 v[152:155], v[136:137], off offset:256
	global_load_dwordx4 v[148:151], v[138:139], off
	global_load_dwordx4 v[144:147], v[138:139], off offset:256
	global_load_dwordx4 v[140:143], v[234:235], off
	s_nop 0
	global_load_dwordx4 v[136:139], v[234:235], off offset:256
	global_load_dwordx4 v[132:135], v[236:237], off
	global_load_dwordx4 v[128:131], v[236:237], off offset:256
	v_add_u32_e32 v232, s11, v188
	v_ashrrev_i32_e32 v233, 31, v232
	s_and_b64 vcc, exec, s[0:1]
	s_mov_b32 s16, s10
	s_mov_b32 s18, s12
	s_mov_b64 s[20:21], s[4:5]
	s_mov_b64 s[22:23], s[14:15]
	s_mov_b32 s45, s44
	s_waitcnt vmcnt(0)
	v_lshlrev_b32_e32 v234, 16, v198
	v_and_b32_e32 v235, 0xffff0000, v198
	v_lshlrev_b32_e32 v198, 16, v199
	v_and_b32_e32 v199, 0xffff0000, v199
	v_lshlrev_b32_e32 v242, 16, v204
	v_and_b32_e32 v243, 0xffff0000, v204
	v_lshlrev_b32_e32 v236, 16, v200
	v_and_b32_e32 v237, 0xffff0000, v200
	v_lshlrev_b32_e32 v200, 16, v201
	v_and_b32_e32 v201, 0xffff0000, v201
	v_lshlrev_b32_e32 v240, 16, v202
	v_and_b32_e32 v241, 0xffff0000, v202
	v_lshlrev_b32_e32 v202, 16, v203
	v_and_b32_e32 v203, 0xffff0000, v203
	v_lshlrev_b32_e32 v204, 16, v205
	v_and_b32_e32 v205, 0xffff0000, v205
	s_waitcnt lgkmcnt(0)
; __device__ __forceinline__ float bf_lo(unsigned w) { return __uint_as_float(w << 16); }
; __device__ __forceinline__ float bf_hi(unsigned w) { return __uint_as_float(w & 0xffff0000u); }
;     __device__ __forceinline__ void operator()(const f32x4 (&acc)[2][2][4][2], const Unit& u, int ui, int wr, int wc, int fr, int fq) const {
;     ...
;         for (int ai = 0; ai < 2; ++ai)
; #pragma unroll
;             for (int m = 0; m < 4; ++m) { const int rl = rl0 + ai * 128 + m * 16; float* rowp = out + (size_t)(u.pm * 256 + rl) * DM + col0;
;                 const float r2 = tab[ui * 256 + rl];
; #pragma unroll
;                 for (int bj = 0; bj < 2; ++bj) { const u32x4 x = xv[ai][m][bj];
;                     const f32x4 x0 = {bf_lo(x.x), bf_hi(x.x), bf_lo(x.y), bf_hi(x.y)}, x1 = {bf_lo(x.z), bf_hi(x.z), bf_lo(x.w), bf_hi(x.w)};
;                     *(f32x4*)(rowp + bj * 128) = acc[ai][bj][m][0] * r2 + x0; *(f32x4*)(rowp + bj * 128 + 4) = acc[ai][bj][m][1] * r2 + x1; } }
	v_pk_fma_f32 v[126:127], v[126:127], v[230:231], v[198:199] op_sel_hi:[1,0,1]
	v_pk_fma_f32 v[124:125], v[124:125], v[230:231], v[234:235] op_sel_hi:[1,0,1]
	v_pk_fma_f32 v[108:109], v[108:109], v[230:231], v[242:243] op_sel_hi:[1,0,1]
	v_pk_fma_f32 v[122:123], v[122:123], v[230:231], v[200:201] op_sel_hi:[1,0,1]
	v_pk_fma_f32 v[120:121], v[120:121], v[230:231], v[236:237] op_sel_hi:[1,0,1]
	v_pk_fma_f32 v[118:119], v[118:119], v[230:231], v[202:203] op_sel_hi:[1,0,1]
	v_pk_fma_f32 v[116:117], v[116:117], v[230:231], v[240:241] op_sel_hi:[1,0,1]
	v_pk_fma_f32 v[110:111], v[110:111], v[230:231], v[204:205] op_sel_hi:[1,0,1]
	global_store_dwordx4 v[238:239], v[124:127], off nt
	global_store_dwordx4 v[238:239], v[120:123], off offset:16 nt
	global_store_dwordx4 v[238:239], v[116:119], off offset:512 nt
	global_store_dwordx4 v[238:239], v[108:111], off offset:528 nt
	v_mov_b32_e32 v122, v231
	v_lshlrev_b32_e32 v118, 16, v208
	v_lshlrev_b64 v[108:109], 12, v[232:233]
	v_lshl_add_u64 v[108:109], s[26:27], 0, v[108:109]
	v_lshl_add_u64 v[116:117], v[108:109], 0, v[176:177]
	v_lshlrev_b32_e32 v108, 16, v206
	v_and_b32_e32 v109, 0xffff0000, v206
	v_lshlrev_b32_e32 v110, 16, v207
	v_and_b32_e32 v111, 0xffff0000, v207
	v_pk_fma_f32 v[110:111], v[114:115], v[122:123], v[110:111] op_sel_hi:[1,0,1]
	v_pk_fma_f32 v[108:109], v[112:113], v[122:123], v[108:109] op_sel_hi:[1,0,1]
	global_store_dwordx4 v[116:117], v[108:111], off nt
	v_and_b32_e32 v119, 0xffff0000, v208
	v_lshlrev_b32_e32 v120, 16, v209
	v_lshlrev_b32_e32 v108, 16, v212
	v_and_b32_e32 v109, 0xffff0000, v212
	v_lshlrev_b32_e32 v110, 16, v213
	v_and_b32_e32 v111, 0xffff0000, v213
	v_pk_fma_f32 v[98:99], v[98:99], v[122:123], v[110:111] op_sel_hi:[1,0,1]
	v_pk_fma_f32 v[96:97], v[96:97], v[122:123], v[108:109] op_sel_hi:[1,0,1]
	v_and_b32_e32 v121, 0xffff0000, v209
	global_store_dwordx4 v[116:117], v[96:99], off offset:528 nt
	ds_read2_b32 v[98:99], v196 offset0:32 offset1:48
	v_pk_fma_f32 v[106:107], v[106:107], v[122:123], v[120:121] op_sel_hi:[1,0,1]
	v_pk_fma_f32 v[104:105], v[104:105], v[122:123], v[118:119] op_sel_hi:[1,0,1]
	v_add_u32_e32 v96, s11, v189
	global_store_dwordx4 v[116:117], v[104:107], off offset:16 nt
	v_ashrrev_i32_e32 v97, 31, v96
	v_lshlrev_b64 v[96:97], 12, v[96:97]
	v_lshlrev_b32_e32 v104, 16, v210
	v_and_b32_e32 v105, 0xffff0000, v210
	v_lshlrev_b32_e32 v106, 16, v211
	v_and_b32_e32 v107, 0xffff0000, v211
	v_pk_fma_f32 v[102:103], v[102:103], v[122:123], v[106:107] op_sel_hi:[1,0,1]
	v_pk_fma_f32 v[100:101], v[100:101], v[122:123], v[104:105] op_sel_hi:[1,0,1]
	global_store_dwordx4 v[116:117], v[100:103], off offset:512 nt
	v_lshl_add_u64 v[96:97], s[26:27], 0, v[96:97]
	v_lshl_add_u64 v[96:97], v[96:97], 0, v[176:177]
	v_lshlrev_b32_e32 v100, 16, v214
	v_and_b32_e32 v101, 0xffff0000, v214
	v_lshlrev_b32_e32 v102, 16, v215
	v_and_b32_e32 v103, 0xffff0000, v215
	s_waitcnt lgkmcnt(0)
	v_pk_fma_f32 v[94:95], v[94:95], v[98:99], v[102:103] op_sel_hi:[1,0,1]
	v_pk_fma_f32 v[92:93], v[92:93], v[98:99], v[100:101] op_sel_hi:[1,0,1]
	global_store_dwordx4 v[96:97], v[92:95], off nt
	v_lshlrev_b32_e32 v104, 16, v216
	v_and_b32_e32 v105, 0xffff0000, v216
	v_lshlrev_b32_e32 v92, 16, v220
	v_and_b32_e32 v93, 0xffff0000, v220
	v_lshlrev_b32_e32 v94, 16, v221
	v_and_b32_e32 v95, 0xffff0000, v221
	v_lshlrev_b32_e32 v106, 16, v217
	v_and_b32_e32 v107, 0xffff0000, v217
	v_pk_fma_f32 v[82:83], v[82:83], v[98:99], v[94:95] op_sel_hi:[1,0,1]
	v_pk_fma_f32 v[80:81], v[80:81], v[98:99], v[92:93] op_sel_hi:[1,0,1]
	v_pk_fma_f32 v[90:91], v[90:91], v[98:99], v[106:107] op_sel_hi:[1,0,1]
	v_pk_fma_f32 v[88:89], v[88:89], v[98:99], v[104:105] op_sel_hi:[1,0,1]
	global_store_dwordx4 v[96:97], v[80:83], off offset:528 nt
	global_store_dwordx4 v[96:97], v[88:91], off offset:16 nt
	s_nop 0
	v_add_u32_e32 v80, s11, v190
	v_lshlrev_b32_e32 v88, 16, v218
	v_and_b32_e32 v89, 0xffff0000, v218
	v_lshlrev_b32_e32 v90, 16, v219
	v_and_b32_e32 v91, 0xffff0000, v219
	v_ashrrev_i32_e32 v81, 31, v80
	v_pk_fma_f32 v[86:87], v[86:87], v[98:99], v[90:91] op_sel_hi:[1,0,1]
	v_pk_fma_f32 v[84:85], v[84:85], v[98:99], v[88:89] op_sel_hi:[1,0,1]
	v_lshlrev_b64 v[80:81], 12, v[80:81]
	global_store_dwordx4 v[96:97], v[84:87], off offset:512 nt
	v_lshl_add_u64 v[80:81], s[26:27], 0, v[80:81]
	v_lshlrev_b32_e32 v82, 16, v222
	v_and_b32_e32 v83, 0xffff0000, v222
	v_lshlrev_b32_e32 v84, 16, v223
	v_and_b32_e32 v85, 0xffff0000, v223
	v_mov_b32_e32 v90, v99
	v_lshl_add_u64 v[80:81], v[80:81], 0, v[176:177]
	v_pk_fma_f32 v[78:79], v[78:79], v[90:91], v[84:85] op_sel_hi:[1,0,1]
	v_pk_fma_f32 v[76:77], v[76:77], v[90:91], v[82:83] op_sel_hi:[1,0,1]
	global_store_dwordx4 v[80:81], v[76:79], off nt
	v_lshlrev_b32_e32 v86, 16, v224
	v_and_b32_e32 v87, 0xffff0000, v224
	v_lshlrev_b32_e32 v76, 16, v228
	v_and_b32_e32 v77, 0xffff0000, v228
	v_lshlrev_b32_e32 v78, 16, v229
	v_and_b32_e32 v79, 0xffff0000, v229
	v_pk_fma_f32 v[66:67], v[66:67], v[90:91], v[78:79] op_sel_hi:[1,0,1]
	v_pk_fma_f32 v[64:65], v[64:65], v[90:91], v[76:77] op_sel_hi:[1,0,1]
	v_lshlrev_b32_e32 v88, 16, v225
	v_and_b32_e32 v89, 0xffff0000, v225
	global_store_dwordx4 v[80:81], v[64:67], off offset:528 nt
	ds_read2_b32 v[66:67], v196 offset0:128 offset1:144
	v_pk_fma_f32 v[74:75], v[74:75], v[90:91], v[88:89] op_sel_hi:[1,0,1]
	v_pk_fma_f32 v[72:73], v[72:73], v[90:91], v[86:87] op_sel_hi:[1,0,1]
	global_store_dwordx4 v[80:81], v[72:75], off offset:16 nt
	v_lshlrev_b64 v[64:65], 12, v[184:185]
	v_lshl_add_u64 v[64:65], s[26:27], 0, v[64:65]
	v_lshlrev_b32_e32 v72, 16, v226
	v_and_b32_e32 v73, 0xffff0000, v226
	v_lshlrev_b32_e32 v74, 16, v227
	v_and_b32_e32 v75, 0xffff0000, v227
	v_pk_fma_f32 v[70:71], v[70:71], v[90:91], v[74:75] op_sel_hi:[1,0,1]
	v_pk_fma_f32 v[68:69], v[68:69], v[90:91], v[72:73] op_sel_hi:[1,0,1]
	global_store_dwordx4 v[80:81], v[68:71], off offset:512 nt
	v_lshl_add_u64 v[64:65], v[64:65], 0, v[176:177]
	v_lshlrev_b32_e32 v72, 16, v158
	v_lshlrev_b32_e32 v68, 16, v156
	v_and_b32_e32 v69, 0xffff0000, v156
	v_lshlrev_b32_e32 v70, 16, v157
	v_and_b32_e32 v71, 0xffff0000, v157
	v_and_b32_e32 v73, 0xffff0000, v158
	v_lshlrev_b32_e32 v74, 16, v159
	v_and_b32_e32 v75, 0xffff0000, v159
	s_waitcnt lgkmcnt(0)
; __device__ __forceinline__ float bf_lo(unsigned w) { return __uint_as_float(w << 16); }
; __device__ __forceinline__ float bf_hi(unsigned w) { return __uint_as_float(w & 0xffff0000u); }
; template <class Epi, class Ptrs>
; __device__ __forceinline__ void gemm_phase(LAS unsigned char* lds, const int K, const StaticOrder& S, const Ptrs& P, const Epi& E) {
;     ...
;         E(acc, cur, ui, wr, wc, fr, fq);
;         if (!has_next) break;
;     __device__ __forceinline__ void operator()(const f32x4 (&acc)[2][2][4][2], const Unit& u, int ui, int wr, int wc, int fr, int fq) const {
;     ...
;         for (int ai = 0; ai < 2; ++ai)
; #pragma unroll
;             for (int m = 0; m < 4; ++m) { const int rl = rl0 + ai * 128 + m * 16; float* rowp = out + (size_t)(u.pm * 256 + rl) * DM + col0;
;                 const float r2 = tab[ui * 256 + rl];
; #pragma unroll
;                 for (int bj = 0; bj < 2; ++bj) { const u32x4 x = xv[ai][m][bj];
;                     const f32x4 x0 = {bf_lo(x.x), bf_hi(x.x), bf_lo(x.y), bf_hi(x.y)}, x1 = {bf_lo(x.z), bf_hi(x.z), bf_lo(x.w), bf_hi(x.w)};
;                     *(f32x4*)(rowp + bj * 128) = acc[ai][bj][m][0] * r2 + x0; *(f32x4*)(rowp + bj * 128 + 4) = acc[ai][bj][m][1] * r2 + x1; } }
	v_pk_fma_f32 v[62:63], v[62:63], v[66:67], v[70:71] op_sel_hi:[1,0,1]
	v_pk_fma_f32 v[60:61], v[60:61], v[66:67], v[68:69] op_sel_hi:[1,0,1]
	global_store_dwordx4 v[64:65], v[60:63], off nt
	v_pk_fma_f32 v[58:59], v[58:59], v[66:67], v[74:75] op_sel_hi:[1,0,1]
	v_pk_fma_f32 v[56:57], v[56:57], v[66:67], v[72:73] op_sel_hi:[1,0,1]
	v_lshlrev_b32_e32 v60, 16, v154
	v_and_b32_e32 v61, 0xffff0000, v154
	v_lshlrev_b32_e32 v62, 16, v155
	v_and_b32_e32 v63, 0xffff0000, v155
	global_store_dwordx4 v[64:65], v[56:59], off offset:16 nt
	v_pk_fma_f32 v[46:47], v[46:47], v[66:67], v[62:63] op_sel_hi:[1,0,1]
	v_pk_fma_f32 v[44:45], v[44:45], v[66:67], v[60:61] op_sel_hi:[1,0,1]
	v_lshlrev_b32_e32 v56, 16, v152
	v_and_b32_e32 v57, 0xffff0000, v152
	v_lshlrev_b32_e32 v58, 16, v153
	v_and_b32_e32 v59, 0xffff0000, v153
	v_pk_fma_f32 v[54:55], v[54:55], v[66:67], v[58:59] op_sel_hi:[1,0,1]
	v_pk_fma_f32 v[52:53], v[52:53], v[66:67], v[56:57] op_sel_hi:[1,0,1]
	global_store_dwordx4 v[64:65], v[44:47], off offset:528 nt
	global_store_dwordx4 v[64:65], v[52:55], off offset:512 nt
	v_lshlrev_b32_e32 v56, 16, v151
	v_lshlrev_b64 v[44:45], 12, v[182:183]
	v_lshl_add_u64 v[44:45], s[26:27], 0, v[44:45]
	v_lshlrev_b32_e32 v54, 16, v150
	v_and_b32_e32 v55, 0xffff0000, v150
	v_and_b32_e32 v57, 0xffff0000, v151
	v_mov_b32_e32 v58, v67
	v_lshl_add_u64 v[52:53], v[44:45], 0, v[176:177]
	v_pk_fma_f32 v[42:43], v[42:43], v[58:59], v[56:57] op_sel_hi:[1,0,1]
	v_pk_fma_f32 v[40:41], v[40:41], v[58:59], v[54:55] op_sel_hi:[1,0,1]
	v_lshlrev_b32_e32 v44, 16, v148
	v_and_b32_e32 v45, 0xffff0000, v148
	v_lshlrev_b32_e32 v46, 16, v149
	v_and_b32_e32 v47, 0xffff0000, v149
	global_store_dwordx4 v[52:53], v[40:43], off offset:16 nt
	v_pk_fma_f32 v[46:47], v[50:51], v[58:59], v[46:47] op_sel_hi:[1,0,1]
	v_pk_fma_f32 v[44:45], v[48:49], v[58:59], v[44:45] op_sel_hi:[1,0,1]
	v_lshlrev_b32_e32 v40, 16, v144
	v_and_b32_e32 v41, 0xffff0000, v144
	v_lshlrev_b32_e32 v42, 16, v145
	v_and_b32_e32 v43, 0xffff0000, v145
	v_pk_fma_f32 v[38:39], v[38:39], v[58:59], v[42:43] op_sel_hi:[1,0,1]
	v_pk_fma_f32 v[36:37], v[36:37], v[58:59], v[40:41] op_sel_hi:[1,0,1]
	global_store_dwordx4 v[52:53], v[44:47], off nt
	global_store_dwordx4 v[52:53], v[36:39], off offset:512 nt
	ds_read2_b32 v[38:39], v196 offset0:160 offset1:176
	v_lshlrev_b32_e32 v44, 16, v146
	v_and_b32_e32 v45, 0xffff0000, v146
	v_lshlrev_b32_e32 v46, 16, v147
	v_and_b32_e32 v47, 0xffff0000, v147
	v_pk_fma_f32 v[30:31], v[30:31], v[58:59], v[46:47] op_sel_hi:[1,0,1]
	v_pk_fma_f32 v[28:29], v[28:29], v[58:59], v[44:45] op_sel_hi:[1,0,1]
	global_store_dwordx4 v[52:53], v[28:31], off offset:528 nt
	v_lshlrev_b32_e32 v40, 16, v142
	v_and_b32_e32 v41, 0xffff0000, v142
	v_lshlrev_b64 v[28:29], 12, v[180:181]
	v_lshl_add_u64 v[28:29], s[26:27], 0, v[28:29]
	v_lshl_add_u64 v[36:37], v[28:29], 0, v[176:177]
	v_lshlrev_b32_e32 v28, 16, v140
	v_and_b32_e32 v29, 0xffff0000, v140
	v_lshlrev_b32_e32 v30, 16, v141
	v_and_b32_e32 v31, 0xffff0000, v141
	s_waitcnt lgkmcnt(0)
	v_pk_fma_f32 v[30:31], v[34:35], v[38:39], v[30:31] op_sel_hi:[1,0,1]
	v_pk_fma_f32 v[28:29], v[32:33], v[38:39], v[28:29] op_sel_hi:[1,0,1]
	v_lshlrev_b32_e32 v42, 16, v143
	v_and_b32_e32 v43, 0xffff0000, v143
	global_store_dwordx4 v[36:37], v[28:31], off nt
	v_pk_fma_f32 v[26:27], v[26:27], v[38:39], v[42:43] op_sel_hi:[1,0,1]
	v_pk_fma_f32 v[24:25], v[24:25], v[38:39], v[40:41] op_sel_hi:[1,0,1]
	v_lshlrev_b32_e32 v28, 16, v138
	v_and_b32_e32 v29, 0xffff0000, v138
	v_lshlrev_b32_e32 v30, 16, v139
	v_and_b32_e32 v31, 0xffff0000, v139
	v_pk_fma_f32 v[14:15], v[14:15], v[38:39], v[30:31] op_sel_hi:[1,0,1]
	v_pk_fma_f32 v[12:13], v[12:13], v[38:39], v[28:29] op_sel_hi:[1,0,1]
	global_store_dwordx4 v[36:37], v[24:27], off offset:16 nt
	global_store_dwordx4 v[36:37], v[12:15], off offset:528 nt
	s_nop 0
	v_lshlrev_b32_e32 v24, 16, v136
	v_and_b32_e32 v25, 0xffff0000, v136
	v_lshlrev_b32_e32 v26, 16, v137
	v_and_b32_e32 v27, 0xffff0000, v137
	v_lshlrev_b64 v[12:13], 12, v[178:179]
	v_pk_fma_f32 v[22:23], v[22:23], v[38:39], v[26:27] op_sel_hi:[1,0,1]
	v_pk_fma_f32 v[20:21], v[20:21], v[38:39], v[24:25] op_sel_hi:[1,0,1]
	v_lshl_add_u64 v[12:13], s[26:27], 0, v[12:13]
	global_store_dwordx4 v[36:37], v[20:23], off offset:512 nt
	v_lshlrev_b32_e32 v14, 16, v133
	v_and_b32_e32 v15, 0xffff0000, v133
	v_lshl_add_u64 v[20:21], v[12:13], 0, v[176:177]
	v_lshlrev_b32_e32 v12, 16, v132
	v_and_b32_e32 v13, 0xffff0000, v132
	v_lshlrev_b32_e32 v22, 16, v134
	v_and_b32_e32 v23, 0xffff0000, v134
	v_lshlrev_b32_e32 v24, 16, v135
	v_and_b32_e32 v25, 0xffff0000, v135
	v_mov_b32_e32 v26, v39
	v_pk_fma_f32 v[14:15], v[18:19], v[26:27], v[14:15] op_sel_hi:[1,0,1]
	v_pk_fma_f32 v[12:13], v[16:17], v[26:27], v[12:13] op_sel_hi:[1,0,1]
	v_pk_fma_f32 v[10:11], v[10:11], v[26:27], v[24:25] op_sel_hi:[1,0,1]
	v_pk_fma_f32 v[8:9], v[8:9], v[26:27], v[22:23] op_sel_hi:[1,0,1]
	global_store_dwordx4 v[20:21], v[12:15], off nt
	global_store_dwordx4 v[20:21], v[8:11], off offset:16 nt
	s_nop 0
	v_lshlrev_b32_e32 v12, 16, v130
	v_lshlrev_b32_e32 v8, 16, v128
	v_and_b32_e32 v9, 0xffff0000, v128
	v_lshlrev_b32_e32 v10, 16, v129
	v_and_b32_e32 v11, 0xffff0000, v129
	v_and_b32_e32 v13, 0xffff0000, v130
	v_lshlrev_b32_e32 v14, 16, v131
	v_and_b32_e32 v15, 0xffff0000, v131
	v_pk_fma_f32 v[6:7], v[6:7], v[26:27], v[10:11] op_sel_hi:[1,0,1]
	v_pk_fma_f32 v[4:5], v[4:5], v[26:27], v[8:9] op_sel_hi:[1,0,1]
	v_pk_fma_f32 v[2:3], v[2:3], v[26:27], v[14:15] op_sel_hi:[1,0,1]
	v_pk_fma_f32 v[0:1], v[0:1], v[26:27], v[12:13] op_sel_hi:[1,0,1]
	global_store_dwordx4 v[20:21], v[4:7], off offset:512 nt
	global_store_dwordx4 v[20:21], v[0:3], off offset:528 nt
	s_cbranch_vccz .LBB0_517
	s_waitcnt vmcnt(0)
	s_setprio 0
	s_cmpk_gt_u32 s33, 0xff
	s_cbranch_scc1 .LBB0_526
	s_barrier
